# g3 epilogue: 32 global_store_short per lane -> LDS-staged 4x global_store_dwordx4 (plus ds_read_b64 split in attention PV)
# baseline (speedup 1.0000x reference)
; DI void gla_g3_block(const P& p, int cgi, int hh, char* smem) {
;     ...
;   if (dir == 0) {
; #pragma unroll
;     for (int j = 0; j < 8; ++j)
; #pragma unroll
;       for (int r = 0; r < 4; ++r) o[j][r] += ob[(16 * slab + 4 * q4 + r) * 132 + 16 * j + r16];
;     float ss[4];
; #pragma unroll
;     for (int r = 0; r < 4; ++r) {
;       float sq = 0.f;
; #pragma unroll
;       for (int j = 0; j < 8; ++j) sq += o[j][r] * o[j][r];
;       sq += __shfl_xor(sq, 1); sq += __shfl_xor(sq, 2); sq += __shfl_xor(sq, 4); sq += __shfl_xor(sq, 8);
;       ss[r] = rsqrtf(sq * (1.f / 128.f) + EPS);
;     ...
;       const float gw = p.gla_norm_w[v];
.LBB0_573:
	s_andn2_b64 vcc, exec, vcc
	s_waitcnt lgkmcnt(0)
	s_barrier
	s_cbranch_vccnz .LBB0_568
	v_or_b32_e32 v140, s6, v37
	v_mad_u64_u32 v[50:51], s[4:5], v140, s54, v[38:39]
	ds_read2_b32 v[112:113], v50 offset1:16
	ds_read2_b32 v[114:115], v50 offset0:132 offset1:148
	v_add_u32_e32 v51, 0x400, v50
	ds_read2_b32 v[116:117], v51 offset0:8 offset1:24
	ds_read2_b32 v[118:119], v51 offset0:140 offset1:156
	ds_read2_b32 v[52:53], v50 offset0:32 offset1:48
	ds_read2_b32 v[56:57], v50 offset0:164 offset1:180
	ds_read2_b32 v[120:121], v51 offset0:40 offset1:56
	ds_read2_b32 v[122:123], v51 offset0:172 offset1:188
	ds_read2_b32 v[124:125], v50 offset0:64 offset1:80
	ds_read2_b32 v[126:127], v50 offset0:196 offset1:212
	ds_read2_b32 v[128:129], v51 offset0:72 offset1:88
	ds_read2_b32 v[58:59], v51 offset0:204 offset1:220
	ds_read2_b32 v[130:131], v50 offset0:96 offset1:112
	ds_read2_b32 v[132:133], v50 offset0:228 offset1:244
	ds_read2_b32 v[134:135], v51 offset0:104 offset1:120
	ds_read2_b32 v[60:61], v51 offset0:236 offset1:252
	v_and_b32_e32 v51, 64, v79
	v_xor_b32_e32 v50, 1, v79
	v_add_u32_e32 v111, 64, v51
	v_cmp_lt_i32_e32 vcc, v50, v111
	v_mov_b32_e32 v51, v28
	v_mov_b32_e32 v28, v25
	v_cndmask_b32_e32 v50, v79, v50, vcc
	v_lshlrev_b32_e32 v141, 2, v50
	v_mov_b32_e32 v50, v24
	s_waitcnt lgkmcnt(10)
	v_pk_add_f32 v[24:25], v[28:29], v[56:57]
	v_mov_b32_e32 v28, v112
	v_mov_b32_e32 v29, v114
	v_mov_b32_e32 v114, v113
	v_pk_add_f32 v[54:55], v[50:51], v[52:53]
	v_pk_add_f32 v[56:57], v[16:17], v[28:29]
	v_pk_add_f32 v[28:29], v[12:13], v[114:115]
	v_pk_mul_f32 v[136:137], v[54:55], v[54:55]
	v_mov_b32_e32 v50, v20
	v_mov_b32_e32 v51, v4
	v_pk_mul_f32 v[138:139], v[24:25], v[24:25]
	v_pk_mul_f32 v[12:13], v[28:29], v[28:29]
	v_mov_b32_e32 v4, v21
	s_waitcnt lgkmcnt(7)
	v_pk_add_f32 v[52:53], v[50:51], v[124:125]
	v_pk_fma_f32 v[16:17], v[56:57], v[56:57], v[12:13]
	s_waitcnt lgkmcnt(6)
	v_pk_add_f32 v[12:13], v[4:5], v[126:127]
	v_mov_b32_e32 v20, v138
	v_mov_b32_e32 v21, v136
	v_pk_mul_f32 v[124:125], v[52:53], v[52:53]
	v_mov_b32_e32 v50, v8
	v_mov_b32_e32 v51, v0
	v_pk_mul_f32 v[4:5], v[12:13], v[12:13]
	v_mov_b32_e32 v0, v9
	v_pk_add_f32 v[16:17], v[16:17], v[20:21] op_sel:[1,0] op_sel_hi:[0,1]
	v_mov_b32_e32 v136, v139
	s_waitcnt lgkmcnt(3)
	v_pk_add_f32 v[50:51], v[50:51], v[130:131]
	s_waitcnt lgkmcnt(2)
	v_pk_add_f32 v[0:1], v[0:1], v[132:133]
	v_pk_add_f32 v[16:17], v[16:17], v[136:137]
	v_mov_b32_e32 v20, v4
	v_mov_b32_e32 v21, v124
	v_pk_mul_f32 v[130:131], v[50:51], v[50:51]
	v_pk_mul_f32 v[8:9], v[0:1], v[0:1]
	v_pk_add_f32 v[16:17], v[16:17], v[20:21]
	v_mov_b32_e32 v124, v5
	v_pk_add_f32 v[4:5], v[16:17], v[124:125]
	v_mov_b32_e32 v16, v8
	v_mov_b32_e32 v17, v130
	v_pk_add_f32 v[4:5], v[4:5], v[16:17]
	v_mov_b32_e32 v130, v9
	v_pk_add_f32 v[4:5], v[4:5], v[130:131]
	ds_bpermute_b32 v9, v141, v5
	ds_bpermute_b32 v8, v141, v4
	global_load_dword v113, v[44:45], off
	v_xor_b32_e32 v16, 2, v79
	v_cmp_lt_i32_e32 vcc, v16, v111
	s_lshl_b32 s44, s57, 1
	s_waitcnt lgkmcnt(0)
	v_pk_add_f32 v[4:5], v[4:5], v[8:9]
	v_cndmask_b32_e32 v16, v79, v16, vcc
	v_lshlrev_b32_e32 v112, 2, v16
	ds_bpermute_b32 v9, v112, v5
	ds_bpermute_b32 v8, v112, v4
	v_xor_b32_e32 v16, 4, v79
	v_cmp_lt_i32_e32 vcc, v16, v111
	s_waitcnt lgkmcnt(0)
	v_pk_add_f32 v[4:5], v[4:5], v[8:9]
	v_cndmask_b32_e32 v16, v79, v16, vcc
	v_lshlrev_b32_e32 v130, 2, v16
	ds_bpermute_b32 v9, v130, v5
	ds_bpermute_b32 v8, v130, v4
	v_xor_b32_e32 v16, 8, v79
	v_cmp_lt_i32_e32 vcc, v16, v111
	s_waitcnt lgkmcnt(0)
	v_pk_add_f32 v[114:115], v[4:5], v[8:9]
	v_mov_b32_e32 v5, v30
	v_mov_b32_e32 v30, v27
	v_cndmask_b32_e32 v16, v79, v16, vcc
	v_mov_b32_e32 v4, v26
	v_pk_add_f32 v[20:21], v[30:31], v[122:123]
	v_mov_b32_e32 v31, v118
	v_mov_b32_e32 v118, v117
	v_lshlrev_b32_e32 v111, 2, v16
	v_pk_add_f32 v[16:17], v[4:5], v[120:121]
	v_mov_b32_e32 v30, v116
	v_pk_add_f32 v[14:15], v[14:15], v[118:119]
	v_pk_mul_f32 v[120:121], v[16:17], v[16:17]
	v_mov_b32_e32 v4, v22
	v_mov_b32_e32 v5, v6
	v_pk_mul_f32 v[26:27], v[20:21], v[20:21]
	v_pk_add_f32 v[18:19], v[18:19], v[30:31]
	v_pk_mul_f32 v[30:31], v[14:15], v[14:15]
	v_mov_b32_e32 v6, v23
	v_pk_add_f32 v[8:9], v[4:5], v[128:129]
	v_pk_fma_f32 v[30:31], v[18:19], v[18:19], v[30:31]
	v_pk_add_f32 v[6:7], v[6:7], v[58:59]
	v_mov_b32_e32 v58, v26
	v_mov_b32_e32 v59, v120
	v_pk_mul_f32 v[126:127], v[8:9], v[8:9]
	v_mov_b32_e32 v4, v10
	v_mov_b32_e32 v5, v2
	v_pk_mul_f32 v[22:23], v[6:7], v[6:7]
	v_mov_b32_e32 v2, v11
	v_pk_add_f32 v[30:31], v[30:31], v[58:59] op_sel:[1,0] op_sel_hi:[0,1]
	v_mov_b32_e32 v120, v27
	v_pk_add_f32 v[4:5], v[4:5], v[134:135]
	v_pk_add_f32 v[2:3], v[2:3], v[60:61]
	v_pk_add_f32 v[26:27], v[30:31], v[120:121]
	v_mov_b32_e32 v30, v22
	v_mov_b32_e32 v31, v126
	v_pk_mul_f32 v[128:129], v[4:5], v[4:5]
	v_pk_mul_f32 v[10:11], v[2:3], v[2:3]
	v_pk_add_f32 v[26:27], v[26:27], v[30:31]
	v_mov_b32_e32 v126, v23
	v_pk_add_f32 v[22:23], v[26:27], v[126:127]
	v_mov_b32_e32 v26, v10
	v_mov_b32_e32 v27, v128
	v_pk_add_f32 v[22:23], v[22:23], v[26:27]
	v_mov_b32_e32 v128, v11
	v_pk_add_f32 v[10:11], v[22:23], v[128:129]
	ds_bpermute_b32 v23, v141, v11
	ds_bpermute_b32 v22, v141, v10
	ds_bpermute_b32 v125, v111, v115
	ds_bpermute_b32 v124, v111, v114
	v_mov_b64_e32 v[30:31], s[48:49]
	s_waitcnt lgkmcnt(2)
	v_pk_add_f32 v[10:11], v[10:11], v[22:23]
	ds_bpermute_b32 v23, v112, v11
	ds_bpermute_b32 v22, v112, v10
	s_waitcnt lgkmcnt(2)
	v_pk_add_f32 v[26:27], v[114:115], v[124:125]
	s_waitcnt lgkmcnt(0)
	v_pk_add_f32 v[10:11], v[10:11], v[22:23]
	ds_bpermute_b32 v23, v130, v11
	ds_bpermute_b32 v22, v130, v10
	v_pk_fma_f32 v[26:27], v[26:27], s[46:47], v[30:31] op_sel_hi:[1,0,0]
	s_waitcnt lgkmcnt(0)
; DI float b2f(unsigned b) { return __uint_as_float(b << 16); }
; DI float fexp(float x) { return __builtin_amdgcn_exp2f(x * LOG2E); }
; DI void gla_g3_block(const P& p, int cgi, int hh, char* smem) {
;     ...
;       ss[r] = rsqrtf(sq * (1.f / 128.f) + EPS);
;     }
;     bf16_t* mixin = (bf16_t*)(p.ws + OFF_MIXIN);
; #pragma unroll
;     for (int j = 0; j < 8; ++j) {
;       const int v = 16 * j + r16;
;       const float gw = p.gla_norm_w[v];
; #pragma unroll
;       for (int r = 0; r < 4; ++r) {
;         const int tok = t0 + 16 * slab + 4 * q4 + r;
;         float g = b2f(graw[j][r]);
;         float val = o[j][r] * ss[r] * gw * (g / (1.f + fexp(-g)));
;         mixin[(long)tok * 1024 + hh * 128 + v] = f2b(val);
	v_pk_add_f32 v[10:11], v[10:11], v[22:23]
	v_mul_f32_e32 v58, 0x4b800000, v27
	v_cmp_gt_f32_e32 vcc, s55, v27
	ds_bpermute_b32 v23, v111, v11
	ds_bpermute_b32 v22, v111, v10
	v_cndmask_b32_e32 v27, v27, v58, vcc
	v_rsq_f32_e32 v27, v27
	v_mul_f32_e32 v58, 0x4b800000, v26
	v_cmp_gt_f32_e64 s[4:5], s55, v26
	s_waitcnt lgkmcnt(0)
	v_pk_add_f32 v[10:11], v[10:11], v[22:23]
	v_cndmask_b32_e64 v26, v26, v58, s[4:5]
	v_mul_f32_e32 v58, 0x45800000, v27
	v_pk_fma_f32 v[10:11], v[10:11], s[46:47], v[30:31] op_sel_hi:[1,0,0]
	v_cndmask_b32_e32 v112, v27, v58, vcc
	v_mul_f32_e32 v22, 0x4b800000, v11
	v_cmp_gt_f32_e32 vcc, s55, v11
	v_cmp_gt_f32_e64 s[6:7], s55, v10
	v_rsq_f32_e32 v26, v26
	v_cndmask_b32_e32 v11, v11, v22, vcc
	v_mul_f32_e32 v22, 0x4b800000, v10
	v_rsq_f32_e32 v11, v11
	v_cndmask_b32_e64 v10, v10, v22, s[6:7]
	v_rsq_f32_e32 v10, v10
	v_mul_f32_e32 v27, 0x45800000, v26
	v_mul_f32_e32 v22, 0x45800000, v11
	v_cndmask_b32_e32 v61, v11, v22, vcc
	v_mul_f32_e32 v11, 0x45800000, v10
	v_cndmask_b32_e64 v60, v10, v11, s[6:7]
	v_mul_f32_e32 v10, 0xbfb8aa3b, v110
	v_exp_f32_e32 v23, v10
	v_cndmask_b32_e64 v111, v26, v27, s[4:5]
	v_mul_f32_e32 v30, v56, v112
	s_waitcnt vmcnt(0)
	v_mul_f32_e32 v30, v30, v113
	v_add_f32_e32 v23, 1.0, v23
	v_div_scale_f32 v27, s[4:5], v23, v23, v110
	v_rcp_f32_e32 v26, v27
	v_or_b32_e32 v22, s50, v140
	v_and_b32_e32 v156, 48, v140
	v_bfe_u32 v157, v140, 2, 2
	v_and_b32_e32 v158, 15, v79
	v_mul_u32_u24_e32 v159, 0x210, v156
	v_add_u32_e32 v159, 16, v159
	v_mul_u32_u24_e32 v160, 0x440, v157
	v_lshl_add_u32 v200, v158, 1, v159
	v_add_u32_e32 v200, v200, v160
	v_mul_u32_u24_e32 v160, 0x110, v157
	v_lshl_add_u32 v201, v158, 4, v159
	v_add_u32_e32 v201, v201, v160
	v_add3_u32 v161, s50, v156, v157
	v_mov_b32_e32 v163, 0
	v_lshlrev_b32_e32 v162, 11, v161
	v_mul_u32_u24_e32 v164, 14, v158
	v_lshl_add_u64 v[202:203], v[46:47], 0, s[44:45]
	v_add_u32_e32 v162, v162, v164
	v_lshl_add_u64 v[202:203], v[202:203], 0, v[162:163]
	global_load_dword v56, v[44:45], off offset:64
	global_load_dword v114, v[44:45], off offset:128
	global_load_dword v115, v[44:45], off offset:192
	global_load_dword v116, v[44:45], off offset:256
	global_load_dword v118, v[44:45], off offset:320
	global_load_dword v119, v[44:45], off offset:384
	global_load_dword v117, v[44:45], off offset:448
	v_lshl_add_u64 v[10:11], v[46:47], 0, s[44:45]
	v_fma_f32 v31, -v27, v26, 1.0
	v_fmac_f32_e32 v26, v31, v26
	v_div_scale_f32 v31, vcc, v110, v23, v110
	v_mul_f32_e32 v58, v31, v26
	v_fma_f32 v59, -v27, v58, v31
	v_fmac_f32_e32 v58, v59, v26
	v_fma_f32 v27, -v27, v58, v31
	v_div_fmas_f32 v26, v27, v26, v58
	v_div_fixup_f32 v23, v26, v23, v110
	v_mul_f32_e32 v26, 0xbfb8aa3b, v109
	v_exp_f32_e32 v31, v26
	v_mul_f32_e32 v23, v23, v30
	v_cvt_pk_bf16_f32 v30, v23, s0
	v_ashrrev_i32_e32 v23, 31, v22
	v_lshlrev_b64 v[26:27], 11, v[22:23]
	v_add_f32_e32 v23, 1.0, v31
	v_lshl_add_u64 v[58:59], v[10:11], 0, v[26:27]
	v_div_scale_f32 v27, s[4:5], v23, v23, v109
	ds_write_b16 v200, v30 offset:0
	v_rcp_f32_e32 v30, v27
	v_mul_f32_e32 v31, v57, v111
	v_or_b32_e32 v26, 1, v22
	v_mul_f32_e32 v31, v113, v31
	v_fma_f32 v57, -v27, v30, 1.0
	v_fmac_f32_e32 v30, v57, v30
	v_div_scale_f32 v57, vcc, v109, v23, v109
	v_mul_f32_e32 v110, v57, v30
	v_fma_f32 v120, -v27, v110, v57
	v_fmac_f32_e32 v110, v120, v30
	v_fma_f32 v27, -v27, v110, v57
	v_div_fmas_f32 v27, v27, v30, v110
	v_mul_f32_e32 v30, 0xbfb8aa3b, v108
	v_exp_f32_e32 v57, v30
	v_div_fixup_f32 v23, v27, v23, v109
	v_ashrrev_i32_e32 v27, 31, v26
	v_mul_f32_e32 v23, v23, v31
	v_lshlrev_b64 v[26:27], 11, v[26:27]
	v_cvt_pk_bf16_f32 v23, v23, s0
	v_lshl_add_u64 v[30:31], v[10:11], 0, v[26:27]
	ds_write_b16 v200, v23 offset:272
	v_add_f32_e32 v23, 1.0, v57
	v_div_scale_f32 v27, s[4:5], v23, v23, v108
	v_rcp_f32_e32 v57, v27
	v_mul_f32_e32 v18, v18, v61
	v_mul_f32_e32 v18, v113, v18
	v_or_b32_e32 v26, 2, v22
	v_fma_f32 v109, -v27, v57, 1.0
	v_fmac_f32_e32 v57, v109, v57
	v_div_scale_f32 v109, vcc, v108, v23, v108
	v_mul_f32_e32 v110, v109, v57
	v_fma_f32 v120, -v27, v110, v109
	v_fmac_f32_e32 v110, v120, v57
	v_fma_f32 v27, -v27, v110, v109
	v_div_fmas_f32 v27, v27, v57, v110
	v_div_fixup_f32 v23, v27, v23, v108
	v_mul_f32_e32 v18, v23, v18
	v_mul_f32_e32 v23, 0xbfb8aa3b, v107
	v_exp_f32_e32 v23, v23
	v_ashrrev_i32_e32 v27, 31, v26
	v_lshlrev_b64 v[26:27], 11, v[26:27]
	v_cvt_pk_bf16_f32 v18, v18, s0
	v_add_f32_e32 v23, 1.0, v23
	v_div_scale_f32 v57, s[4:5], v23, v23, v107
	v_rcp_f32_e32 v108, v57
	v_lshl_add_u64 v[26:27], v[10:11], 0, v[26:27]
	ds_write_b16 v200, v18 offset:544
	v_or_b32_e32 v18, 3, v22
	v_fma_f32 v22, -v57, v108, 1.0
	v_fmac_f32_e32 v108, v22, v108
	v_div_scale_f32 v22, vcc, v107, v23, v107
	v_mul_f32_e32 v109, v22, v108
	v_fma_f32 v110, -v57, v109, v22
	v_fmac_f32_e32 v109, v110, v108
	v_fma_f32 v22, -v57, v109, v22
	v_mul_f32_e32 v19, v19, v60
	v_div_fmas_f32 v22, v22, v108, v109
	v_mul_f32_e32 v19, v113, v19
	v_div_fixup_f32 v22, v22, v23, v107
	v_mul_f32_e32 v19, v22, v19
	v_cvt_pk_bf16_f32 v22, v19, s0
	v_mul_f32_e32 v19, 0xbfb8aa3b, v106
	v_exp_f32_e32 v23, v19
	v_ashrrev_i32_e32 v19, 31, v18
	v_lshlrev_b64 v[18:19], 11, v[18:19]
	v_lshl_add_u64 v[10:11], v[10:11], 0, v[18:19]
	v_add_f32_e32 v18, 1.0, v23
	v_div_scale_f32 v19, s[4:5], v18, v18, v106
	v_rcp_f32_e32 v23, v19
	ds_write_b16 v200, v22 offset:816
	v_mul_f32_e32 v22, v28, v112
	s_waitcnt vmcnt(0)
; DI float b2f(unsigned b) { return __uint_as_float(b << 16); }
; DI float fexp(float x) { return __builtin_amdgcn_exp2f(x * LOG2E); }
; DI void gla_g3_block(const P& p, int cgi, int hh, char* smem) {
;     ...
;     for (int j = 0; j < 8; ++j) {
;       const int v = 16 * j + r16;
;       const float gw = p.gla_norm_w[v];
; #pragma unroll
;       for (int r = 0; r < 4; ++r) {
;         const int tok = t0 + 16 * slab + 4 * q4 + r;
;         float g = b2f(graw[j][r]);
;         float val = o[j][r] * ss[r] * gw * (g / (1.f + fexp(-g)));
;         mixin[(long)tok * 1024 + hh * 128 + v] = f2b(val);
	v_mul_f32_e32 v22, v22, v56
	v_fma_f32 v28, -v19, v23, 1.0
	v_fmac_f32_e32 v23, v28, v23
	v_div_scale_f32 v28, vcc, v106, v18, v106
	v_mul_f32_e32 v57, v28, v23
	v_fma_f32 v107, -v19, v57, v28
	v_fmac_f32_e32 v57, v107, v23
	v_fma_f32 v19, -v19, v57, v28
	v_div_fmas_f32 v19, v19, v23, v57
	v_mul_f32_e32 v23, 0xbfb8aa3b, v105
	v_exp_f32_e32 v23, v23
	v_div_fixup_f32 v18, v19, v18, v106
	v_mul_f32_e32 v18, v18, v22
	v_cvt_pk_bf16_f32 v18, v18, s0
	v_add_f32_e32 v19, 1.0, v23
	v_div_scale_f32 v22, s[4:5], v19, v19, v105
	v_rcp_f32_e32 v23, v22
	ds_write_b16 v200, v18 offset:32
	v_mul_f32_e32 v18, v29, v111
	v_mul_f32_e32 v18, v18, v56
	v_fma_f32 v28, -v22, v23, 1.0
	v_fmac_f32_e32 v23, v28, v23
	v_div_scale_f32 v28, vcc, v105, v19, v105
	v_mul_f32_e32 v29, v28, v23
	v_fma_f32 v57, -v22, v29, v28
	v_fmac_f32_e32 v29, v57, v23
	v_fma_f32 v22, -v22, v29, v28
	v_div_fmas_f32 v22, v22, v23, v29
	v_mul_f32_e32 v23, 0xbfb8aa3b, v104
	v_exp_f32_e32 v23, v23
	v_div_fixup_f32 v19, v22, v19, v105
	v_mul_f32_e32 v18, v19, v18
	v_cvt_pk_bf16_f32 v18, v18, s0
	v_add_f32_e32 v19, 1.0, v23
	v_div_scale_f32 v22, s[4:5], v19, v19, v104
	v_rcp_f32_e32 v23, v22
	ds_write_b16 v200, v18 offset:304
	v_mul_f32_e32 v14, v14, v61
	v_mul_f32_e32 v14, v14, v56
	v_fma_f32 v18, -v22, v23, 1.0
	v_fmac_f32_e32 v23, v18, v23
	v_div_scale_f32 v18, vcc, v104, v19, v104
	v_mul_f32_e32 v28, v18, v23
	v_fma_f32 v29, -v22, v28, v18
	v_fmac_f32_e32 v28, v29, v23
	v_fma_f32 v18, -v22, v28, v18
	v_mul_f32_e32 v22, 0xbfb8aa3b, v103
	v_exp_f32_e32 v22, v22
	v_div_fmas_f32 v18, v18, v23, v28
	v_div_fixup_f32 v18, v18, v19, v104
	v_mul_f32_e32 v14, v18, v14
	v_add_f32_e32 v18, 1.0, v22
	v_div_scale_f32 v19, s[4:5], v18, v18, v103
	v_rcp_f32_e32 v22, v19
	v_cvt_pk_bf16_f32 v14, v14, s0
	ds_write_b16 v200, v14 offset:576
	v_mul_f32_e32 v14, v15, v60
	v_fma_f32 v15, -v19, v22, 1.0
	v_fmac_f32_e32 v22, v15, v22
	v_div_scale_f32 v15, vcc, v103, v18, v103
	v_mul_f32_e32 v23, v15, v22
	v_fma_f32 v28, -v19, v23, v15
	v_fmac_f32_e32 v23, v28, v22
	v_fma_f32 v15, -v19, v23, v15
	v_mul_f32_e32 v19, 0xbfb8aa3b, v102
	v_exp_f32_e32 v19, v19
	v_div_fmas_f32 v15, v15, v22, v23
	v_mul_f32_e32 v14, v56, v14
	v_div_fixup_f32 v15, v15, v18, v103
	v_mul_f32_e32 v14, v15, v14
	v_add_f32_e32 v15, 1.0, v19
	v_div_scale_f32 v18, s[4:5], v15, v15, v102
	v_rcp_f32_e32 v19, v18
	v_cvt_pk_bf16_f32 v14, v14, s0
	ds_write_b16 v200, v14 offset:848
	v_mul_f32_e32 v14, v54, v112
	v_fma_f32 v22, -v18, v19, 1.0
	v_fmac_f32_e32 v19, v22, v19
	v_div_scale_f32 v22, vcc, v102, v15, v102
	v_mul_f32_e32 v23, v22, v19
	v_fma_f32 v28, -v18, v23, v22
	v_fmac_f32_e32 v23, v28, v19
	v_fma_f32 v18, -v18, v23, v22
	v_div_fmas_f32 v18, v18, v19, v23
	v_mul_f32_e32 v19, 0xbfb8aa3b, v101
	v_exp_f32_e32 v19, v19
	s_waitcnt vmcnt(0)
	v_mul_f32_e32 v14, v14, v114
	v_div_fixup_f32 v15, v18, v15, v102
	v_mul_f32_e32 v14, v15, v14
	v_add_f32_e32 v15, 1.0, v19
	v_div_scale_f32 v18, s[4:5], v15, v15, v101
	v_rcp_f32_e32 v19, v18
	v_cvt_pk_bf16_f32 v14, v14, s0
	ds_write_b16 v200, v14 offset:64
	v_mul_f32_e32 v14, v24, v111
	v_fma_f32 v22, -v18, v19, 1.0
	v_fmac_f32_e32 v19, v22, v19
	v_div_scale_f32 v22, vcc, v101, v15, v101
	v_mul_f32_e32 v23, v22, v19
	v_fma_f32 v24, -v18, v23, v22
	v_fmac_f32_e32 v23, v24, v19
	v_fma_f32 v18, -v18, v23, v22
	v_div_fmas_f32 v18, v18, v19, v23
	v_mul_f32_e32 v19, 0xbfb8aa3b, v100
	v_exp_f32_e32 v19, v19
	v_mul_f32_e32 v14, v14, v114
	v_div_fixup_f32 v15, v18, v15, v101
	v_mul_f32_e32 v14, v15, v14
	v_add_f32_e32 v15, 1.0, v19
	v_div_scale_f32 v18, s[4:5], v15, v15, v100
	v_rcp_f32_e32 v19, v18
	v_cvt_pk_bf16_f32 v14, v14, s0
	ds_write_b16 v200, v14 offset:336
	v_mul_f32_e32 v14, v16, v61
	v_fma_f32 v16, -v18, v19, 1.0
	v_fmac_f32_e32 v19, v16, v19
	v_div_scale_f32 v16, vcc, v100, v15, v100
	v_mul_f32_e32 v22, v16, v19
	v_fma_f32 v23, -v18, v22, v16
	v_fmac_f32_e32 v22, v23, v19
	v_fma_f32 v16, -v18, v22, v16
	v_mul_f32_e32 v18, 0xbfb8aa3b, v99
	v_exp_f32_e32 v18, v18
	v_div_fmas_f32 v16, v16, v19, v22
	v_mul_f32_e32 v14, v14, v114
	v_div_fixup_f32 v15, v16, v15, v100
	v_mul_f32_e32 v14, v15, v14
	v_add_f32_e32 v15, 1.0, v18
	v_div_scale_f32 v16, s[4:5], v15, v15, v99
	v_rcp_f32_e32 v18, v16
	v_cvt_pk_bf16_f32 v14, v14, s0
	ds_write_b16 v200, v14 offset:608
	v_mul_f32_e32 v14, v20, v60
	v_fma_f32 v19, -v16, v18, 1.0
	v_fmac_f32_e32 v18, v19, v18
	v_div_scale_f32 v19, vcc, v99, v15, v99
	v_mul_f32_e32 v20, v19, v18
	v_fma_f32 v22, -v16, v20, v19
	v_fmac_f32_e32 v20, v22, v18
	v_fma_f32 v16, -v16, v20, v19
	v_div_fmas_f32 v16, v16, v18, v20
	v_mul_f32_e32 v18, 0xbfb8aa3b, v98
	v_exp_f32_e32 v18, v18
	v_mul_f32_e32 v14, v14, v114
	v_div_fixup_f32 v15, v16, v15, v99
	v_mul_f32_e32 v14, v15, v14
	v_add_f32_e32 v15, 1.0, v18
	v_div_scale_f32 v16, s[4:5], v15, v15, v98
	v_rcp_f32_e32 v18, v16
	v_cvt_pk_bf16_f32 v14, v14, s0
	ds_write_b16 v200, v14 offset:880
	v_mul_f32_e32 v14, v55, v112
	v_fma_f32 v19, -v16, v18, 1.0
	v_fmac_f32_e32 v18, v19, v18
	v_div_scale_f32 v19, vcc, v98, v15, v98
	v_mul_f32_e32 v20, v19, v18
	v_fma_f32 v22, -v16, v20, v19
	v_fmac_f32_e32 v20, v22, v18
	v_fma_f32 v16, -v16, v20, v19
	v_div_fmas_f32 v16, v16, v18, v20
	v_mul_f32_e32 v18, 0xbfb8aa3b, v97
	v_exp_f32_e32 v18, v18
	s_waitcnt vmcnt(0)
; DI float b2f(unsigned b) { return __uint_as_float(b << 16); }
; DI float fexp(float x) { return __builtin_amdgcn_exp2f(x * LOG2E); }
; DI void gla_g3_block(const P& p, int cgi, int hh, char* smem) {
;     ...
;     for (int j = 0; j < 8; ++j) {
;       const int v = 16 * j + r16;
;       const float gw = p.gla_norm_w[v];
; #pragma unroll
;       for (int r = 0; r < 4; ++r) {
;         const int tok = t0 + 16 * slab + 4 * q4 + r;
;         float g = b2f(graw[j][r]);
;         float val = o[j][r] * ss[r] * gw * (g / (1.f + fexp(-g)));
;         mixin[(long)tok * 1024 + hh * 128 + v] = f2b(val);
	v_mul_f32_e32 v14, v14, v115
	v_div_fixup_f32 v15, v16, v15, v98
	v_mul_f32_e32 v14, v15, v14
	v_add_f32_e32 v15, 1.0, v18
	v_div_scale_f32 v16, s[4:5], v15, v15, v97
	v_rcp_f32_e32 v18, v16
	v_cvt_pk_bf16_f32 v14, v14, s0
	ds_write_b16 v200, v14 offset:96
	v_mul_f32_e32 v14, v25, v111
	v_fma_f32 v19, -v16, v18, 1.0
	v_fmac_f32_e32 v18, v19, v18
	v_div_scale_f32 v19, vcc, v97, v15, v97
	v_mul_f32_e32 v20, v19, v18
	v_fma_f32 v22, -v16, v20, v19
	v_fmac_f32_e32 v20, v22, v18
	v_fma_f32 v16, -v16, v20, v19
	v_div_fmas_f32 v16, v16, v18, v20
	v_mul_f32_e32 v18, 0xbfb8aa3b, v96
	v_exp_f32_e32 v18, v18
	v_mul_f32_e32 v14, v14, v115
	v_div_fixup_f32 v15, v16, v15, v97
	v_mul_f32_e32 v14, v15, v14
	v_add_f32_e32 v15, 1.0, v18
	v_div_scale_f32 v16, s[4:5], v15, v15, v96
	v_rcp_f32_e32 v18, v16
	v_cvt_pk_bf16_f32 v14, v14, s0
	ds_write_b16 v200, v14 offset:368
	v_mul_f32_e32 v14, v17, v61
	v_fma_f32 v17, -v16, v18, 1.0
	v_fmac_f32_e32 v18, v17, v18
	v_div_scale_f32 v17, vcc, v96, v15, v96
	v_mul_f32_e32 v19, v17, v18
	v_fma_f32 v20, -v16, v19, v17
	v_fmac_f32_e32 v19, v20, v18
	v_fma_f32 v16, -v16, v19, v17
	v_mul_f32_e32 v17, 0xbfb8aa3b, v95
	v_exp_f32_e32 v17, v17
	v_div_fmas_f32 v16, v16, v18, v19
	v_mul_f32_e32 v14, v14, v115
	v_div_fixup_f32 v15, v16, v15, v96
	v_mul_f32_e32 v14, v15, v14
	v_add_f32_e32 v15, 1.0, v17
	v_div_scale_f32 v16, s[4:5], v15, v15, v95
	v_rcp_f32_e32 v17, v16
	v_cvt_pk_bf16_f32 v14, v14, s0
	ds_write_b16 v200, v14 offset:640
	v_mul_f32_e32 v14, v21, v60
	v_fma_f32 v18, -v16, v17, 1.0
	v_fmac_f32_e32 v17, v18, v17
	v_div_scale_f32 v18, vcc, v95, v15, v95
	v_mul_f32_e32 v19, v18, v17
	v_fma_f32 v20, -v16, v19, v18
	v_fmac_f32_e32 v19, v20, v17
	v_fma_f32 v16, -v16, v19, v18
	v_div_fmas_f32 v16, v16, v17, v19
	v_mul_f32_e32 v17, 0xbfb8aa3b, v94
	v_exp_f32_e32 v17, v17
	v_mul_f32_e32 v14, v14, v115
	v_div_fixup_f32 v15, v16, v15, v95
	v_mul_f32_e32 v14, v15, v14
	v_add_f32_e32 v15, 1.0, v17
	v_div_scale_f32 v16, s[4:5], v15, v15, v94
	v_rcp_f32_e32 v17, v16
	v_cvt_pk_bf16_f32 v14, v14, s0
	ds_write_b16 v200, v14 offset:912
	v_mul_f32_e32 v14, v52, v112
	v_fma_f32 v18, -v16, v17, 1.0
	v_fmac_f32_e32 v17, v18, v17
	v_div_scale_f32 v18, vcc, v94, v15, v94
	v_mul_f32_e32 v19, v18, v17
	v_fma_f32 v20, -v16, v19, v18
	v_fmac_f32_e32 v19, v20, v17
	v_fma_f32 v16, -v16, v19, v18
	v_div_fmas_f32 v16, v16, v17, v19
	v_mul_f32_e32 v17, 0xbfb8aa3b, v93
	v_exp_f32_e32 v17, v17
	s_waitcnt vmcnt(0)
	v_mul_f32_e32 v14, v14, v116
	v_div_fixup_f32 v15, v16, v15, v94
	v_mul_f32_e32 v14, v15, v14
	v_add_f32_e32 v15, 1.0, v17
	v_div_scale_f32 v16, s[4:5], v15, v15, v93
	v_rcp_f32_e32 v17, v16
	v_cvt_pk_bf16_f32 v14, v14, s0
	ds_write_b16 v200, v14 offset:128
	v_mul_f32_e32 v12, v12, v111
	v_fma_f32 v14, -v16, v17, 1.0
	v_fmac_f32_e32 v17, v14, v17
	v_div_scale_f32 v14, vcc, v93, v15, v93
	v_mul_f32_e32 v18, v14, v17
	v_fma_f32 v19, -v16, v18, v14
	v_fmac_f32_e32 v18, v19, v17
	v_fma_f32 v14, -v16, v18, v14
	v_mul_f32_e32 v16, 0xbfb8aa3b, v92
	v_exp_f32_e32 v16, v16
	v_div_fmas_f32 v14, v14, v17, v18
	v_mul_f32_e32 v12, v12, v116
	v_div_fixup_f32 v14, v14, v15, v93
	v_mul_f32_e32 v12, v14, v12
	v_add_f32_e32 v14, 1.0, v16
	v_div_scale_f32 v15, s[4:5], v14, v14, v92
	v_rcp_f32_e32 v16, v15
	v_cvt_pk_bf16_f32 v12, v12, s0
	ds_write_b16 v200, v12 offset:400
	v_mul_f32_e32 v8, v8, v61
	v_fma_f32 v12, -v15, v16, 1.0
	v_fmac_f32_e32 v16, v12, v16
	v_div_scale_f32 v12, vcc, v92, v14, v92
	v_mul_f32_e32 v17, v12, v16
	v_fma_f32 v18, -v15, v17, v12
	v_fmac_f32_e32 v17, v18, v16
	v_fma_f32 v12, -v15, v17, v12
	v_mul_f32_e32 v15, 0xbfb8aa3b, v91
	v_exp_f32_e32 v15, v15
	v_div_fmas_f32 v12, v12, v16, v17
	v_mul_f32_e32 v8, v8, v116
	v_div_fixup_f32 v12, v12, v14, v92
	v_mul_f32_e32 v8, v12, v8
	v_add_f32_e32 v12, 1.0, v15
	v_div_scale_f32 v14, s[4:5], v12, v12, v91
	v_rcp_f32_e32 v15, v14
	v_cvt_pk_bf16_f32 v8, v8, s0
	ds_write_b16 v200, v8 offset:672
	v_mul_f32_e32 v6, v6, v60
	v_fma_f32 v8, -v14, v15, 1.0
	v_fmac_f32_e32 v15, v8, v15
	v_div_scale_f32 v8, vcc, v91, v12, v91
	v_mul_f32_e32 v16, v8, v15
	v_fma_f32 v17, -v14, v16, v8
	v_fmac_f32_e32 v16, v17, v15
	v_fma_f32 v8, -v14, v16, v8
	v_mul_f32_e32 v14, 0xbfb8aa3b, v90
	v_exp_f32_e32 v14, v14
	v_div_fmas_f32 v8, v8, v15, v16
	v_mul_f32_e32 v6, v6, v116
	v_div_fixup_f32 v8, v8, v12, v91
	v_mul_f32_e32 v6, v8, v6
	v_add_f32_e32 v8, 1.0, v14
	v_div_scale_f32 v12, s[4:5], v8, v8, v90
	v_rcp_f32_e32 v14, v12
	v_cvt_pk_bf16_f32 v6, v6, s0
	ds_write_b16 v200, v6 offset:944
	v_mul_f32_e32 v6, v53, v112
	v_fma_f32 v15, -v12, v14, 1.0
	v_fmac_f32_e32 v14, v15, v14
	v_div_scale_f32 v15, vcc, v90, v8, v90
	v_mul_f32_e32 v16, v15, v14
	v_fma_f32 v17, -v12, v16, v15
	v_fmac_f32_e32 v16, v17, v14
	v_fma_f32 v12, -v12, v16, v15
	v_div_fmas_f32 v12, v12, v14, v16
	v_mul_f32_e32 v14, 0xbfb8aa3b, v89
	v_exp_f32_e32 v14, v14
	s_waitcnt vmcnt(0)
; DI float b2f(unsigned b) { return __uint_as_float(b << 16); }
; DI float fexp(float x) { return __builtin_amdgcn_exp2f(x * LOG2E); }
; DI void gla_g3_block(const P& p, int cgi, int hh, char* smem) {
;     ...
;     for (int j = 0; j < 8; ++j) {
;       const int v = 16 * j + r16;
;       const float gw = p.gla_norm_w[v];
; #pragma unroll
;       for (int r = 0; r < 4; ++r) {
;         const int tok = t0 + 16 * slab + 4 * q4 + r;
;         float g = b2f(graw[j][r]);
;         float val = o[j][r] * ss[r] * gw * (g / (1.f + fexp(-g)));
;         mixin[(long)tok * 1024 + hh * 128 + v] = f2b(val);
	v_mul_f32_e32 v6, v6, v118
	v_div_fixup_f32 v8, v12, v8, v90
	v_mul_f32_e32 v6, v8, v6
	v_add_f32_e32 v8, 1.0, v14
	v_div_scale_f32 v12, s[4:5], v8, v8, v89
	v_rcp_f32_e32 v14, v12
	v_cvt_pk_bf16_f32 v6, v6, s0
	ds_write_b16 v200, v6 offset:160
	v_mul_f32_e32 v6, v13, v111
	v_fma_f32 v13, -v12, v14, 1.0
	v_fmac_f32_e32 v14, v13, v14
	v_div_scale_f32 v13, vcc, v89, v8, v89
	v_mul_f32_e32 v15, v13, v14
	v_fma_f32 v16, -v12, v15, v13
	v_fmac_f32_e32 v15, v16, v14
	v_fma_f32 v12, -v12, v15, v13
	v_mul_f32_e32 v13, 0xbfb8aa3b, v88
	v_exp_f32_e32 v13, v13
	v_div_fmas_f32 v12, v12, v14, v15
	v_mul_f32_e32 v6, v6, v118
	v_div_fixup_f32 v8, v12, v8, v89
	v_mul_f32_e32 v6, v8, v6
	v_add_f32_e32 v8, 1.0, v13
	v_div_scale_f32 v12, s[4:5], v8, v8, v88
	v_rcp_f32_e32 v13, v12
	v_cvt_pk_bf16_f32 v6, v6, s0
	ds_write_b16 v200, v6 offset:432
	v_mul_f32_e32 v6, v9, v61
	v_fma_f32 v9, -v12, v13, 1.0
	v_fmac_f32_e32 v13, v9, v13
	v_div_scale_f32 v9, vcc, v88, v8, v88
	v_mul_f32_e32 v14, v9, v13
	v_fma_f32 v15, -v12, v14, v9
	v_fmac_f32_e32 v14, v15, v13
	v_fma_f32 v9, -v12, v14, v9
	v_mul_f32_e32 v12, 0xbfb8aa3b, v87
	v_exp_f32_e32 v12, v12
	v_div_fmas_f32 v9, v9, v13, v14
	v_mul_f32_e32 v6, v6, v118
	v_div_fixup_f32 v8, v9, v8, v88
	v_mul_f32_e32 v6, v8, v6
	v_add_f32_e32 v8, 1.0, v12
	v_div_scale_f32 v9, s[4:5], v8, v8, v87
	v_rcp_f32_e32 v12, v9
	v_cvt_pk_bf16_f32 v6, v6, s0
	ds_write_b16 v200, v6 offset:704
	v_mul_f32_e32 v6, v7, v60
	v_fma_f32 v7, -v9, v12, 1.0
	v_fmac_f32_e32 v12, v7, v12
	v_div_scale_f32 v7, vcc, v87, v8, v87
	v_mul_f32_e32 v13, v7, v12
	v_fma_f32 v14, -v9, v13, v7
	v_fmac_f32_e32 v13, v14, v12
	v_fma_f32 v7, -v9, v13, v7
	v_mul_f32_e32 v9, 0xbfb8aa3b, v84
	v_exp_f32_e32 v9, v9
	v_div_fmas_f32 v7, v7, v12, v13
	v_mul_f32_e32 v6, v6, v118
	v_div_fixup_f32 v7, v7, v8, v87
	v_mul_f32_e32 v6, v7, v6
	v_add_f32_e32 v7, 1.0, v9
	v_div_scale_f32 v8, s[4:5], v7, v7, v84
	v_rcp_f32_e32 v9, v8
	v_cvt_pk_bf16_f32 v6, v6, s0
	ds_write_b16 v200, v6 offset:976
	v_mul_f32_e32 v6, v50, v112
	v_fma_f32 v12, -v8, v9, 1.0
	v_fmac_f32_e32 v9, v12, v9
	v_div_scale_f32 v12, vcc, v84, v7, v84
	v_mul_f32_e32 v13, v12, v9
	v_fma_f32 v14, -v8, v13, v12
	v_fmac_f32_e32 v13, v14, v9
	v_fma_f32 v8, -v8, v13, v12
	v_div_fmas_f32 v8, v8, v9, v13
	v_mul_f32_e32 v9, 0xbfb8aa3b, v83
	v_exp_f32_e32 v9, v9
	s_waitcnt vmcnt(0)
	v_mul_f32_e32 v6, v6, v119
	v_div_fixup_f32 v7, v8, v7, v84
	v_mul_f32_e32 v6, v7, v6
	v_add_f32_e32 v7, 1.0, v9
	v_div_scale_f32 v8, s[4:5], v7, v7, v83
	v_rcp_f32_e32 v9, v8
	v_cvt_pk_bf16_f32 v6, v6, s0
	ds_write_b16 v200, v6 offset:192
	v_mul_f32_e32 v0, v0, v111
	v_fma_f32 v6, -v8, v9, 1.0
	v_fmac_f32_e32 v9, v6, v9
	v_div_scale_f32 v6, vcc, v83, v7, v83
	v_mul_f32_e32 v12, v6, v9
	v_fma_f32 v13, -v8, v12, v6
	v_fmac_f32_e32 v12, v13, v9
	v_fma_f32 v6, -v8, v12, v6
	v_mul_f32_e32 v8, 0xbfb8aa3b, v86
	v_exp_f32_e32 v8, v8
	v_div_fmas_f32 v6, v6, v9, v12
	v_mul_f32_e32 v0, v0, v119
	v_div_fixup_f32 v6, v6, v7, v83
	v_mul_f32_e32 v0, v6, v0
	v_add_f32_e32 v6, 1.0, v8
	v_div_scale_f32 v7, s[4:5], v6, v6, v86
	v_rcp_f32_e32 v8, v7
	v_cvt_pk_bf16_f32 v0, v0, s0
	ds_write_b16 v200, v0 offset:464
	v_mul_f32_e32 v0, v4, v61
	v_fma_f32 v4, -v7, v8, 1.0
	v_fmac_f32_e32 v8, v4, v8
	v_div_scale_f32 v4, vcc, v86, v6, v86
	v_mul_f32_e32 v9, v4, v8
	v_fma_f32 v12, -v7, v9, v4
	v_fmac_f32_e32 v9, v12, v8
	v_fma_f32 v4, -v7, v9, v4
	v_mul_f32_e32 v7, 0xbfb8aa3b, v85
	v_exp_f32_e32 v7, v7
	v_div_fmas_f32 v4, v4, v8, v9
	v_mul_f32_e32 v0, v0, v119
	v_div_fixup_f32 v4, v4, v6, v86
	v_mul_f32_e32 v0, v4, v0
	v_add_f32_e32 v4, 1.0, v7
	v_div_scale_f32 v6, s[4:5], v4, v4, v85
	v_rcp_f32_e32 v7, v6
	v_cvt_pk_bf16_f32 v0, v0, s0
	ds_write_b16 v200, v0 offset:736
	v_mul_f32_e32 v0, v2, v60
	v_fma_f32 v2, -v6, v7, 1.0
	v_fmac_f32_e32 v7, v2, v7
	v_div_scale_f32 v2, vcc, v85, v4, v85
	v_mul_f32_e32 v8, v2, v7
	v_fma_f32 v9, -v6, v8, v2
	v_fmac_f32_e32 v8, v9, v7
	v_fma_f32 v2, -v6, v8, v2
	v_mul_f32_e32 v6, 0xbfb8aa3b, v82
	v_exp_f32_e32 v6, v6
	v_div_fmas_f32 v2, v2, v7, v8
	v_mul_f32_e32 v0, v0, v119
	v_div_fixup_f32 v2, v2, v4, v85
	v_mul_f32_e32 v0, v2, v0
	v_add_f32_e32 v2, 1.0, v6
	v_div_scale_f32 v4, s[4:5], v2, v2, v82
	v_rcp_f32_e32 v6, v4
	v_cvt_pk_bf16_f32 v0, v0, s0
	ds_write_b16 v200, v0 offset:1008
	v_mul_f32_e32 v0, v51, v112
	v_fma_f32 v7, -v4, v6, 1.0
	v_fmac_f32_e32 v6, v7, v6
	v_div_scale_f32 v7, vcc, v82, v2, v82
	v_mul_f32_e32 v8, v7, v6
	v_fma_f32 v9, -v4, v8, v7
	v_fmac_f32_e32 v8, v9, v6
	v_fma_f32 v4, -v4, v8, v7
	v_div_fmas_f32 v4, v4, v6, v8
	v_mul_f32_e32 v6, 0xbfb8aa3b, v81
	v_exp_f32_e32 v6, v6
	s_waitcnt vmcnt(0)
; DI float b2f(unsigned b) { return __uint_as_float(b << 16); }
; DI float fexp(float x) { return __builtin_amdgcn_exp2f(x * LOG2E); }
; DI void gla_g3_block(const P& p, int cgi, int hh, char* smem) {
;     ...
;     for (int j = 0; j < 8; ++j) {
;       const int v = 16 * j + r16;
;       const float gw = p.gla_norm_w[v];
; #pragma unroll
;       for (int r = 0; r < 4; ++r) {
;         const int tok = t0 + 16 * slab + 4 * q4 + r;
;         float g = b2f(graw[j][r]);
;         float val = o[j][r] * ss[r] * gw * (g / (1.f + fexp(-g)));
;         mixin[(long)tok * 1024 + hh * 128 + v] = f2b(val);
;       }
;     }
;   }
	v_mul_f32_e32 v0, v0, v117
	v_div_fixup_f32 v2, v4, v2, v82
	v_mul_f32_e32 v0, v2, v0
	v_add_f32_e32 v2, 1.0, v6
	v_div_scale_f32 v4, s[4:5], v2, v2, v81
	v_rcp_f32_e32 v6, v4
	v_cvt_pk_bf16_f32 v0, v0, s0
	ds_write_b16 v200, v0 offset:224
	v_mul_f32_e32 v0, v1, v111
	v_fma_f32 v1, -v4, v6, 1.0
	v_fmac_f32_e32 v6, v1, v6
	v_div_scale_f32 v1, vcc, v81, v2, v81
	v_mul_f32_e32 v7, v1, v6
	v_fma_f32 v8, -v4, v7, v1
	v_fmac_f32_e32 v7, v8, v6
	v_fma_f32 v1, -v4, v7, v1
	v_mul_f32_e32 v4, 0xbfb8aa3b, v80
	v_exp_f32_e32 v4, v4
	v_div_fmas_f32 v1, v1, v6, v7
	v_mul_f32_e32 v0, v0, v117
	v_div_fixup_f32 v1, v1, v2, v81
	v_mul_f32_e32 v0, v1, v0
	v_add_f32_e32 v1, 1.0, v4
	v_div_scale_f32 v2, s[4:5], v1, v1, v80
	v_rcp_f32_e32 v4, v2
	v_cvt_pk_bf16_f32 v0, v0, s0
	ds_write_b16 v200, v0 offset:496
	v_mul_f32_e32 v0, v5, v61
	v_fma_f32 v5, -v2, v4, 1.0
	v_fmac_f32_e32 v4, v5, v4
	v_div_scale_f32 v5, vcc, v80, v1, v80
	v_mul_f32_e32 v6, v5, v4
	v_fma_f32 v7, -v2, v6, v5
	v_fmac_f32_e32 v6, v7, v4
	v_fma_f32 v2, -v2, v6, v5
	v_div_fmas_f32 v2, v2, v4, v6
	v_mul_f32_e32 v4, 0xbfb8aa3b, v34
	v_exp_f32_e32 v4, v4
	v_mul_f32_e32 v0, v0, v117
	v_div_fixup_f32 v1, v2, v1, v80
	v_mul_f32_e32 v0, v1, v0
	v_add_f32_e32 v1, 1.0, v4
	v_div_scale_f32 v2, s[4:5], v1, v1, v34
	v_rcp_f32_e32 v4, v2
	v_cvt_pk_bf16_f32 v0, v0, s0
	ds_write_b16 v200, v0 offset:768
	v_mul_f32_e32 v0, v3, v60
	v_fma_f32 v3, -v2, v4, 1.0
	v_fmac_f32_e32 v4, v3, v4
	v_div_scale_f32 v3, vcc, v34, v1, v34
	v_mul_f32_e32 v5, v3, v4
	v_fma_f32 v6, -v2, v5, v3
	v_fmac_f32_e32 v5, v6, v4
	v_fma_f32 v2, -v2, v5, v3
	v_div_fmas_f32 v2, v2, v4, v5
	v_mul_f32_e32 v0, v0, v117
	v_div_fixup_f32 v1, v2, v1, v34
	v_mul_f32_e32 v0, v1, v0
	v_cvt_pk_bf16_f32 v0, v0, s0
	ds_write_b16 v200, v0 offset:1040
	s_waitcnt lgkmcnt(0)
	ds_read_b128 v[212:215], v201
	ds_read_b128 v[216:219], v201 offset:1088
	ds_read_b128 v[220:223], v201 offset:2176
	ds_read_b128 v[224:227], v201 offset:3264
	v_add_co_u32_e32 v204, vcc, 0x2000, v202
	s_nop 1
	v_addc_co_u32_e32 v205, vcc, 0, v203, vcc
	v_add_co_u32_e32 v206, vcc, 0x4000, v202
	s_nop 1
	v_addc_co_u32_e32 v207, vcc, 0, v203, vcc
	v_add_co_u32_e32 v208, vcc, 0x6000, v202
	s_nop 1
	v_addc_co_u32_e32 v209, vcc, 0, v203, vcc
	s_waitcnt lgkmcnt(3)
	global_store_dwordx4 v[202:203], v[212:215], off
	s_waitcnt lgkmcnt(2)
	global_store_dwordx4 v[204:205], v[216:219], off
	s_waitcnt lgkmcnt(1)
	global_store_dwordx4 v[206:207], v[220:223], off
	s_waitcnt lgkmcnt(0)
	global_store_dwordx4 v[208:209], v[224:227], off
	s_branch .LBB0_568
